# P6 epilogue gates unit: the eight gate-bias values of a lane loaded once per tile instead of 64 load+wait round trips (each of which also sat out the previous store)
# speedup vs baseline: 1.0312x; 1.0131x over previous
.LBB0_645:
	s_lshl_b32 s9, s10, 8
	v_readlane_b32 s10, v254, 60
	s_add_i32 s9, s9, s10
	v_or_b32_e32 v172, s9, v1
	v_ashrrev_i32_e32 v173, 31, v172
	v_lshl_add_u64 v[174:175], v[172:173], 2, s[0:1]
	global_load_dword v130, v[174:175], off
	s_cmp_lg_u32 s8, 0
	s_cselect_b64 s[90:91], -1, 0
	s_cmp_gt_i32 s8, 2
	s_cselect_b64 s[92:93], -1, 0
	s_cmp_gt_u32 s8, 6
	s_cselect_b64 s[84:85], -1, 0
	s_cmp_eq_u32 s8, 6
	s_cselect_b64 s[68:69], -1, 0
	s_cmp_lg_u32 s8, 6
	s_cselect_b64 s[82:83], -1, 0
	s_lshl_b32 s10, s8, 8
	v_readlane_b32 s11, v254, 63
	s_add_i32 s16, s11, s10
	s_cmp_eq_u32 s8, 1
	s_cselect_b64 s[66:67], -1, 0
	s_lshl_b32 s64, s8, 6
	s_ashr_i32 s8, s9, 6
	s_ashr_i32 s9, s8, 31
	s_ashr_i32 s65, s64, 31
	s_lshl_b64 s[88:89], s[8:9], 13
	s_add_u32 s8, s8, s74
	s_addc_u32 s9, s9, 0
	s_lshl_b64 s[86:87], s[8:9], 13
	s_mov_b64 s[8:9], -1
	s_and_b64 vcc, exec, s[90:91]
	s_waitcnt vmcnt(0)
	v_fmamk_f32 v130, v130, 0x3a800000, v155
	v_rsq_f32_e32 v176, v130
	s_cbranch_vccz .LBB0_668
	s_and_b64 vcc, exec, s[92:93]
	s_cbranch_vccz .LBB0_662
	s_and_b64 vcc, exec, s[84:85]
	s_cbranch_vccz .LBB0_655
	s_andn2_b64 vcc, exec, s[34:35]
	s_cbranch_vccnz .LBB0_654
	v_readlane_b32 s8, v254, 58
	v_readlane_b32 s9, v254, 59
	s_nop 1
	v_mov_b64_e32 v[130:131], s[8:9]
	s_movk_i32 s8, 0x90
	v_mad_i64_i32 v[130:131], s[8:9], v172, s8, v[130:131]
	s_mov_b64 s[8:9], exec
	v_readlane_b32 s10, v255, 0
	v_readlane_b32 s11, v255, 1
	s_and_b64 s[10:11], s[8:9], s[10:11]
	s_mov_b64 exec, s[10:11]
	s_cbranch_execz .LBB0_651
	global_load_dwordx4 v[246:249], v[160:161], off
	v_lshlrev_b32_e32 v142, 2, v146
	s_waitcnt vmcnt(0)
	v_mov_b32_e32 v132, v246
	v_fmac_f32_e32 v132, v126, v176
	v_mul_f32_e32 v132, 0xbfb8aa3b, v132
	v_exp_f32_e32 v132, v132
	s_nop 0
	v_add_f32_e32 v177, 1.0, v132
	v_div_scale_f32 v178, s[10:11], v177, v177, 1.0
	v_rcp_f32_e32 v179, v178
	v_lshl_add_u64 v[132:133], v[130:131], 0, v[142:143]
	v_div_scale_f32 v142, vcc, 1.0, v177, 1.0
	v_fma_f32 v180, -v178, v179, 1.0
	v_fmac_f32_e32 v179, v180, v179
	v_mul_f32_e32 v180, v142, v179
	v_fma_f32 v181, -v178, v180, v142
	v_fmac_f32_e32 v180, v181, v179
	v_fma_f32 v142, -v178, v180, v142
	v_div_fmas_f32 v142, v142, v179, v180
	v_div_fixup_f32 v142, v142, v177, 1.0
	global_store_dword v[132:133], v142, off
	v_mov_b32_e32 v142, v247
	v_fmac_f32_e32 v142, v127, v176
	v_mul_f32_e32 v142, 0xbfb8aa3b, v142
	v_exp_f32_e32 v142, v142
	s_nop 0
	v_add_f32_e32 v142, 1.0, v142
	v_div_scale_f32 v177, s[10:11], v142, v142, 1.0
	v_rcp_f32_e32 v178, v177
	v_div_scale_f32 v179, vcc, 1.0, v142, 1.0
	v_fma_f32 v180, -v177, v178, 1.0
	v_fmac_f32_e32 v178, v180, v178
	v_mul_f32_e32 v180, v179, v178
	v_fma_f32 v181, -v177, v180, v179
	v_fmac_f32_e32 v180, v181, v178
	v_fma_f32 v177, -v177, v180, v179
	v_div_fmas_f32 v177, v177, v178, v180
	v_div_fixup_f32 v142, v177, v142, 1.0
	global_store_dword v[132:133], v142, off offset:4
	v_mov_b32_e32 v142, v248
	v_fmac_f32_e32 v142, v128, v176
	v_mul_f32_e32 v142, 0xbfb8aa3b, v142
	v_exp_f32_e32 v142, v142
	s_nop 0
	v_add_f32_e32 v142, 1.0, v142
	v_div_scale_f32 v177, s[10:11], v142, v142, 1.0
	v_rcp_f32_e32 v178, v177
	v_div_scale_f32 v179, vcc, 1.0, v142, 1.0
	v_fma_f32 v180, -v177, v178, 1.0
	v_fmac_f32_e32 v178, v180, v178
	v_mul_f32_e32 v180, v179, v178
	v_fma_f32 v181, -v177, v180, v179
	v_fmac_f32_e32 v180, v181, v178
	v_fma_f32 v177, -v177, v180, v179
	v_div_fmas_f32 v177, v177, v178, v180
	v_div_fixup_f32 v142, v177, v142, 1.0
	global_store_dword v[132:133], v142, off offset:8
	v_mov_b32_e32 v142, v249
	v_fmac_f32_e32 v142, v129, v176
	v_mul_f32_e32 v142, 0xbfb8aa3b, v142
	v_exp_f32_e32 v142, v142
	s_nop 0
	v_add_f32_e32 v142, 1.0, v142
	v_div_scale_f32 v177, s[10:11], v142, v142, 1.0
	v_rcp_f32_e32 v178, v177
	v_div_scale_f32 v179, vcc, 1.0, v142, 1.0
	v_fma_f32 v180, -v177, v178, 1.0
	v_fmac_f32_e32 v178, v180, v178
	v_mul_f32_e32 v180, v179, v178
	v_fma_f32 v181, -v177, v180, v179
	v_fmac_f32_e32 v180, v181, v178
	v_fma_f32 v177, -v177, v180, v179
	v_div_fmas_f32 v177, v177, v178, v180
	v_div_fixup_f32 v142, v177, v142, 1.0
	global_store_dword v[132:133], v142, off offset:12
.LBB0_651:
	s_or_b64 exec, exec, s[8:9]
	s_mov_b64 s[8:9], exec
	v_readlane_b32 s10, v255, 2
	v_readlane_b32 s11, v255, 3
	s_and_b64 s[10:11], s[8:9], s[10:11]
	s_mov_b64 exec, s[10:11]
	s_cbranch_execz .LBB0_653
	global_load_dwordx4 v[250:253], v[160:161], off offset:16
	v_lshlrev_b32_e32 v142, 2, v146
	v_lshl_add_u64 v[130:131], v[130:131], 0, v[142:143]
	s_waitcnt vmcnt(0)
	v_mov_b32_e32 v132, v250
	v_fmac_f32_e32 v132, v122, v176
	v_mul_f32_e32 v132, 0xbfb8aa3b, v132
	v_exp_f32_e32 v132, v132
	s_nop 0
	v_add_f32_e32 v132, 1.0, v132
	v_div_scale_f32 v133, s[10:11], v132, v132, 1.0
	v_rcp_f32_e32 v177, v133
	v_div_scale_f32 v142, vcc, 1.0, v132, 1.0
	v_fma_f32 v178, -v133, v177, 1.0
	v_fmac_f32_e32 v177, v178, v177
	v_mul_f32_e32 v178, v142, v177
	v_fma_f32 v179, -v133, v178, v142
	v_fmac_f32_e32 v178, v179, v177
	v_fma_f32 v133, -v133, v178, v142
	v_div_fmas_f32 v133, v133, v177, v178
	v_div_fixup_f32 v132, v133, v132, 1.0
	global_store_dword v[130:131], v132, off offset:16
	v_mov_b32_e32 v132, v251
	v_fmac_f32_e32 v132, v123, v176
	v_mul_f32_e32 v132, 0xbfb8aa3b, v132
	v_exp_f32_e32 v132, v132
	s_nop 0
	v_add_f32_e32 v132, 1.0, v132
	v_div_scale_f32 v133, s[10:11], v132, v132, 1.0
	v_rcp_f32_e32 v142, v133
	v_div_scale_f32 v177, vcc, 1.0, v132, 1.0
	v_fma_f32 v178, -v133, v142, 1.0
	v_fmac_f32_e32 v142, v178, v142
	v_mul_f32_e32 v178, v177, v142
	v_fma_f32 v179, -v133, v178, v177
	v_fmac_f32_e32 v178, v179, v142
	v_fma_f32 v133, -v133, v178, v177
	v_div_fmas_f32 v133, v133, v142, v178
	v_div_fixup_f32 v132, v133, v132, 1.0
	global_store_dword v[130:131], v132, off offset:20
	v_mov_b32_e32 v132, v252
	v_fmac_f32_e32 v132, v124, v176
	v_mul_f32_e32 v132, 0xbfb8aa3b, v132
	v_exp_f32_e32 v132, v132
	s_nop 0
	v_add_f32_e32 v132, 1.0, v132
	v_div_scale_f32 v133, s[10:11], v132, v132, 1.0
	v_rcp_f32_e32 v142, v133
	v_div_scale_f32 v177, vcc, 1.0, v132, 1.0
	v_fma_f32 v178, -v133, v142, 1.0
	v_fmac_f32_e32 v142, v178, v142
	v_mul_f32_e32 v178, v177, v142
	v_fma_f32 v179, -v133, v178, v177
	v_fmac_f32_e32 v178, v179, v142
	v_fma_f32 v133, -v133, v178, v177
	v_div_fmas_f32 v133, v133, v142, v178
	v_div_fixup_f32 v132, v133, v132, 1.0
	global_store_dword v[130:131], v132, off offset:24
	v_mov_b32_e32 v132, v253
	v_fmac_f32_e32 v132, v125, v176
	v_mul_f32_e32 v132, 0xbfb8aa3b, v132
	v_exp_f32_e32 v132, v132
	s_nop 0
	v_add_f32_e32 v132, 1.0, v132
	v_div_scale_f32 v133, s[10:11], v132, v132, 1.0
	v_rcp_f32_e32 v142, v133
	v_div_scale_f32 v177, vcc, 1.0, v132, 1.0
	v_fma_f32 v178, -v133, v142, 1.0
	v_fmac_f32_e32 v142, v178, v142
	v_mul_f32_e32 v178, v177, v142
	v_fma_f32 v179, -v133, v178, v177
	v_fmac_f32_e32 v178, v179, v142
	v_fma_f32 v133, -v133, v178, v177
	v_div_fmas_f32 v133, v133, v142, v178
	v_div_fixup_f32 v132, v133, v132, 1.0
	global_store_dword v[130:131], v132, off offset:28

.LBB0_670:
	v_or_b32_e32 v120, 16, v172
	v_ashrrev_i32_e32 v121, 31, v120
	v_lshl_add_u64 v[114:115], v[120:121], 2, s[0:1]
	global_load_dword v114, v[114:115], off
	v_cndmask_b32_e64 v115, 0, 1, s[90:91]
	v_cmp_ne_u32_e64 s[10:11], 1, v115
	s_andn2_b64 vcc, exec, s[90:91]
	s_waitcnt vmcnt(0)
	v_fmamk_f32 v114, v114, 0x3a800000, v155
	v_rsq_f32_e32 v118, v114
	v_cndmask_b32_e64 v114, 0, 1, s[92:93]
	v_cmp_ne_u32_e64 s[8:9], 1, v114
	s_cbranch_vccnz .LBB0_841
	s_and_b64 vcc, exec, s[8:9]
	s_mov_b64 s[12:13], -1
	s_cbranch_vccnz .LBB0_687
	s_andn2_b64 vcc, exec, s[84:85]
	s_cbranch_vccnz .LBB0_680
	s_andn2_b64 vcc, exec, s[34:35]
	s_cbranch_vccnz .LBB0_679
	v_readlane_b32 s12, v254, 58
	v_readlane_b32 s13, v254, 59
	v_readlane_b32 s44, v255, 0
	v_readlane_b32 s45, v255, 1
	v_mov_b64_e32 v[114:115], s[12:13]
	s_movk_i32 s12, 0x90
	v_mad_i64_i32 v[114:115], s[12:13], v120, s12, v[114:115]
	s_and_saveexec_b64 s[12:13], s[44:45]
	s_cbranch_execz .LBB0_676
	v_mov_b32_e32 v116, v246
	v_lshlrev_b32_e32 v142, 2, v146
	v_fmac_f32_e32 v116, v110, v118
	v_mul_f32_e32 v116, 0xbfb8aa3b, v116
	v_exp_f32_e32 v116, v116
	s_nop 0
	v_add_f32_e32 v119, 1.0, v116
	v_div_scale_f32 v122, s[90:91], v119, v119, 1.0
	v_rcp_f32_e32 v123, v122
	v_div_scale_f32 v124, vcc, 1.0, v119, 1.0
	v_lshl_add_u64 v[116:117], v[114:115], 0, v[142:143]
	v_fma_f32 v125, -v122, v123, 1.0
	v_fmac_f32_e32 v123, v125, v123
	v_mul_f32_e32 v125, v124, v123
	v_fma_f32 v126, -v122, v125, v124
	v_fmac_f32_e32 v125, v126, v123
	v_fma_f32 v122, -v122, v125, v124
	v_div_fmas_f32 v122, v122, v123, v125
	v_div_fixup_f32 v119, v122, v119, 1.0
	global_store_dword v[116:117], v119, off
	v_mov_b32_e32 v119, v247
	v_fmac_f32_e32 v119, v111, v118
	v_mul_f32_e32 v119, 0xbfb8aa3b, v119
	v_exp_f32_e32 v119, v119
	s_nop 0
	v_add_f32_e32 v119, 1.0, v119
	v_div_scale_f32 v122, s[90:91], v119, v119, 1.0
	v_rcp_f32_e32 v123, v122
	v_div_scale_f32 v124, vcc, 1.0, v119, 1.0
	v_fma_f32 v125, -v122, v123, 1.0
	v_fmac_f32_e32 v123, v125, v123
	v_mul_f32_e32 v125, v124, v123
	v_fma_f32 v126, -v122, v125, v124
	v_fmac_f32_e32 v125, v126, v123
	v_fma_f32 v122, -v122, v125, v124
	v_div_fmas_f32 v122, v122, v123, v125
	v_div_fixup_f32 v119, v122, v119, 1.0
	global_store_dword v[116:117], v119, off offset:4
	v_mov_b32_e32 v119, v248
	v_fmac_f32_e32 v119, v112, v118
	v_mul_f32_e32 v119, 0xbfb8aa3b, v119
	v_exp_f32_e32 v119, v119
	s_nop 0
	v_add_f32_e32 v119, 1.0, v119
	v_div_scale_f32 v122, s[90:91], v119, v119, 1.0
	v_rcp_f32_e32 v123, v122
	v_div_scale_f32 v124, vcc, 1.0, v119, 1.0
	v_fma_f32 v125, -v122, v123, 1.0
	v_fmac_f32_e32 v123, v125, v123
	v_mul_f32_e32 v125, v124, v123
	v_fma_f32 v126, -v122, v125, v124
	v_fmac_f32_e32 v125, v126, v123
	v_fma_f32 v122, -v122, v125, v124
	v_div_fmas_f32 v122, v122, v123, v125
	v_div_fixup_f32 v119, v122, v119, 1.0
	global_store_dword v[116:117], v119, off offset:8
	v_mov_b32_e32 v119, v249
	v_fmac_f32_e32 v119, v113, v118
	v_mul_f32_e32 v119, 0xbfb8aa3b, v119
	v_exp_f32_e32 v119, v119
	s_nop 0
	v_add_f32_e32 v119, 1.0, v119
	v_div_scale_f32 v122, s[90:91], v119, v119, 1.0
	v_rcp_f32_e32 v123, v122
	v_div_scale_f32 v124, vcc, 1.0, v119, 1.0
	v_fma_f32 v125, -v122, v123, 1.0
	v_fmac_f32_e32 v123, v125, v123
	v_mul_f32_e32 v125, v124, v123
	v_fma_f32 v126, -v122, v125, v124
	v_fmac_f32_e32 v125, v126, v123
	v_fma_f32 v122, -v122, v125, v124
	v_div_fmas_f32 v122, v122, v123, v125
	v_div_fixup_f32 v119, v122, v119, 1.0
	global_store_dword v[116:117], v119, off offset:12
.LBB0_676:
	s_or_b64 exec, exec, s[12:13]
	v_readlane_b32 s44, v255, 2
	v_readlane_b32 s45, v255, 3
	s_and_saveexec_b64 s[12:13], s[44:45]
	s_cbranch_execz .LBB0_678
	v_mov_b32_e32 v116, v250
	v_lshlrev_b32_e32 v142, 2, v146
	v_lshl_add_u64 v[114:115], v[114:115], 0, v[142:143]
	v_fmac_f32_e32 v116, v106, v118
	v_mul_f32_e32 v116, 0xbfb8aa3b, v116
	v_exp_f32_e32 v116, v116
	s_nop 0
	v_add_f32_e32 v116, 1.0, v116
	v_div_scale_f32 v117, s[90:91], v116, v116, 1.0
	v_rcp_f32_e32 v119, v117
	v_div_scale_f32 v122, vcc, 1.0, v116, 1.0
	v_fma_f32 v123, -v117, v119, 1.0
	v_fmac_f32_e32 v119, v123, v119
	v_mul_f32_e32 v123, v122, v119
	v_fma_f32 v124, -v117, v123, v122
	v_fmac_f32_e32 v123, v124, v119
	v_fma_f32 v117, -v117, v123, v122
	v_div_fmas_f32 v117, v117, v119, v123
	v_div_fixup_f32 v116, v117, v116, 1.0
	global_store_dword v[114:115], v116, off offset:16
	v_mov_b32_e32 v116, v251
	v_fmac_f32_e32 v116, v107, v118
	v_mul_f32_e32 v116, 0xbfb8aa3b, v116
	v_exp_f32_e32 v116, v116
	s_nop 0
	v_add_f32_e32 v116, 1.0, v116
	v_div_scale_f32 v117, s[90:91], v116, v116, 1.0
	v_rcp_f32_e32 v119, v117
	v_div_scale_f32 v122, vcc, 1.0, v116, 1.0
	v_fma_f32 v123, -v117, v119, 1.0
	v_fmac_f32_e32 v119, v123, v119
	v_mul_f32_e32 v123, v122, v119
	v_fma_f32 v124, -v117, v123, v122
	v_fmac_f32_e32 v123, v124, v119
	v_fma_f32 v117, -v117, v123, v122
	v_div_fmas_f32 v117, v117, v119, v123
	v_div_fixup_f32 v116, v117, v116, 1.0
	global_store_dword v[114:115], v116, off offset:20
	v_mov_b32_e32 v116, v252
	v_fmac_f32_e32 v116, v108, v118
	v_mul_f32_e32 v116, 0xbfb8aa3b, v116
	v_exp_f32_e32 v116, v116
	s_nop 0
	v_add_f32_e32 v116, 1.0, v116
	v_div_scale_f32 v117, s[90:91], v116, v116, 1.0
	v_rcp_f32_e32 v119, v117
	v_div_scale_f32 v122, vcc, 1.0, v116, 1.0
	v_fma_f32 v123, -v117, v119, 1.0
	v_fmac_f32_e32 v119, v123, v119
	v_mul_f32_e32 v123, v122, v119
	v_fma_f32 v124, -v117, v123, v122
	v_fmac_f32_e32 v123, v124, v119
	v_fma_f32 v117, -v117, v123, v122
	v_div_fmas_f32 v117, v117, v119, v123
	v_div_fixup_f32 v116, v117, v116, 1.0
	global_store_dword v[114:115], v116, off offset:24
	v_mov_b32_e32 v116, v253
	v_fmac_f32_e32 v116, v109, v118
	v_mul_f32_e32 v116, 0xbfb8aa3b, v116
	v_exp_f32_e32 v116, v116
	s_nop 0
	v_add_f32_e32 v116, 1.0, v116
	v_div_scale_f32 v117, s[90:91], v116, v116, 1.0
	v_rcp_f32_e32 v119, v117
	v_div_scale_f32 v122, vcc, 1.0, v116, 1.0
	v_fma_f32 v123, -v117, v119, 1.0
	v_fmac_f32_e32 v119, v123, v119
	v_mul_f32_e32 v123, v122, v119
	v_fma_f32 v124, -v117, v123, v122
	v_fmac_f32_e32 v123, v124, v119
	v_fma_f32 v117, -v117, v123, v122
	v_div_fmas_f32 v117, v117, v119, v123
	v_div_fixup_f32 v116, v117, v116, 1.0
	global_store_dword v[114:115], v116, off offset:28

.LBB0_694:
	v_or_b32_e32 v104, 32, v172
	v_ashrrev_i32_e32 v105, 31, v104
	v_lshl_add_u64 v[98:99], v[104:105], 2, s[0:1]
	global_load_dword v98, v[98:99], off
	s_and_b64 vcc, exec, s[10:11]
	s_waitcnt vmcnt(0)
	v_fmamk_f32 v98, v98, 0x3a800000, v155
	v_rsq_f32_e32 v102, v98
	s_cbranch_vccnz .LBB0_842
	s_and_b64 vcc, exec, s[8:9]
	s_mov_b64 s[12:13], -1
	s_cbranch_vccnz .LBB0_711
	s_andn2_b64 vcc, exec, s[84:85]
	s_cbranch_vccnz .LBB0_704
	s_andn2_b64 vcc, exec, s[34:35]
	s_cbranch_vccnz .LBB0_703
	v_readlane_b32 s12, v254, 58
	v_readlane_b32 s13, v254, 59
	v_readlane_b32 s44, v255, 0
	v_readlane_b32 s45, v255, 1
	v_mov_b64_e32 v[98:99], s[12:13]
	s_movk_i32 s12, 0x90
	v_mad_i64_i32 v[98:99], s[12:13], v104, s12, v[98:99]
	s_and_saveexec_b64 s[12:13], s[44:45]
	s_cbranch_execz .LBB0_700
	v_mov_b32_e32 v100, v246
	v_lshlrev_b32_e32 v142, 2, v146
	v_fmac_f32_e32 v100, v94, v102
	v_mul_f32_e32 v100, 0xbfb8aa3b, v100
	v_exp_f32_e32 v100, v100
	s_nop 0
	v_add_f32_e32 v103, 1.0, v100
	v_div_scale_f32 v106, s[90:91], v103, v103, 1.0
	v_rcp_f32_e32 v107, v106
	v_div_scale_f32 v108, vcc, 1.0, v103, 1.0
	v_lshl_add_u64 v[100:101], v[98:99], 0, v[142:143]
	v_fma_f32 v109, -v106, v107, 1.0
	v_fmac_f32_e32 v107, v109, v107
	v_mul_f32_e32 v109, v108, v107
	v_fma_f32 v110, -v106, v109, v108
	v_fmac_f32_e32 v109, v110, v107
	v_fma_f32 v106, -v106, v109, v108
	v_div_fmas_f32 v106, v106, v107, v109
	v_div_fixup_f32 v103, v106, v103, 1.0
	global_store_dword v[100:101], v103, off
	v_mov_b32_e32 v103, v247
	v_fmac_f32_e32 v103, v95, v102
	v_mul_f32_e32 v103, 0xbfb8aa3b, v103
	v_exp_f32_e32 v103, v103
	s_nop 0
	v_add_f32_e32 v103, 1.0, v103
	v_div_scale_f32 v106, s[90:91], v103, v103, 1.0
	v_rcp_f32_e32 v107, v106
	v_div_scale_f32 v108, vcc, 1.0, v103, 1.0
	v_fma_f32 v109, -v106, v107, 1.0
	v_fmac_f32_e32 v107, v109, v107
	v_mul_f32_e32 v109, v108, v107
	v_fma_f32 v110, -v106, v109, v108
	v_fmac_f32_e32 v109, v110, v107
	v_fma_f32 v106, -v106, v109, v108
	v_div_fmas_f32 v106, v106, v107, v109
	v_div_fixup_f32 v103, v106, v103, 1.0
	global_store_dword v[100:101], v103, off offset:4
	v_mov_b32_e32 v103, v248
	v_fmac_f32_e32 v103, v96, v102
	v_mul_f32_e32 v103, 0xbfb8aa3b, v103
	v_exp_f32_e32 v103, v103
	s_nop 0
	v_add_f32_e32 v103, 1.0, v103
	v_div_scale_f32 v106, s[90:91], v103, v103, 1.0
	v_rcp_f32_e32 v107, v106
	v_div_scale_f32 v108, vcc, 1.0, v103, 1.0
	v_fma_f32 v109, -v106, v107, 1.0
	v_fmac_f32_e32 v107, v109, v107
	v_mul_f32_e32 v109, v108, v107
	v_fma_f32 v110, -v106, v109, v108
	v_fmac_f32_e32 v109, v110, v107
	v_fma_f32 v106, -v106, v109, v108
	v_div_fmas_f32 v106, v106, v107, v109
	v_div_fixup_f32 v103, v106, v103, 1.0
	global_store_dword v[100:101], v103, off offset:8
	v_mov_b32_e32 v103, v249
	v_fmac_f32_e32 v103, v97, v102
	v_mul_f32_e32 v103, 0xbfb8aa3b, v103
	v_exp_f32_e32 v103, v103
	s_nop 0
	v_add_f32_e32 v103, 1.0, v103
	v_div_scale_f32 v106, s[90:91], v103, v103, 1.0
	v_rcp_f32_e32 v107, v106
	v_div_scale_f32 v108, vcc, 1.0, v103, 1.0
	v_fma_f32 v109, -v106, v107, 1.0
	v_fmac_f32_e32 v107, v109, v107
	v_mul_f32_e32 v109, v108, v107
	v_fma_f32 v110, -v106, v109, v108
	v_fmac_f32_e32 v109, v110, v107
	v_fma_f32 v106, -v106, v109, v108
	v_div_fmas_f32 v106, v106, v107, v109
	v_div_fixup_f32 v103, v106, v103, 1.0
	global_store_dword v[100:101], v103, off offset:12
.LBB0_700:
	s_or_b64 exec, exec, s[12:13]
	v_readlane_b32 s44, v255, 2
	v_readlane_b32 s45, v255, 3
	s_and_saveexec_b64 s[12:13], s[44:45]
	s_cbranch_execz .LBB0_702
	v_mov_b32_e32 v100, v250
	v_lshlrev_b32_e32 v142, 2, v146
	v_lshl_add_u64 v[98:99], v[98:99], 0, v[142:143]
	v_fmac_f32_e32 v100, v90, v102
	v_mul_f32_e32 v100, 0xbfb8aa3b, v100
	v_exp_f32_e32 v100, v100
	s_nop 0
	v_add_f32_e32 v100, 1.0, v100
	v_div_scale_f32 v101, s[90:91], v100, v100, 1.0
	v_rcp_f32_e32 v103, v101
	v_div_scale_f32 v106, vcc, 1.0, v100, 1.0
	v_fma_f32 v107, -v101, v103, 1.0
	v_fmac_f32_e32 v103, v107, v103
	v_mul_f32_e32 v107, v106, v103
	v_fma_f32 v108, -v101, v107, v106
	v_fmac_f32_e32 v107, v108, v103
	v_fma_f32 v101, -v101, v107, v106
	v_div_fmas_f32 v101, v101, v103, v107
	v_div_fixup_f32 v100, v101, v100, 1.0
	global_store_dword v[98:99], v100, off offset:16
	v_mov_b32_e32 v100, v251
	v_fmac_f32_e32 v100, v91, v102
	v_mul_f32_e32 v100, 0xbfb8aa3b, v100
	v_exp_f32_e32 v100, v100
	s_nop 0
	v_add_f32_e32 v100, 1.0, v100
	v_div_scale_f32 v101, s[90:91], v100, v100, 1.0
	v_rcp_f32_e32 v103, v101
	v_div_scale_f32 v106, vcc, 1.0, v100, 1.0
	v_fma_f32 v107, -v101, v103, 1.0
	v_fmac_f32_e32 v103, v107, v103
	v_mul_f32_e32 v107, v106, v103
	v_fma_f32 v108, -v101, v107, v106
	v_fmac_f32_e32 v107, v108, v103
	v_fma_f32 v101, -v101, v107, v106
	v_div_fmas_f32 v101, v101, v103, v107
	v_div_fixup_f32 v100, v101, v100, 1.0
	global_store_dword v[98:99], v100, off offset:20
	v_mov_b32_e32 v100, v252
	v_fmac_f32_e32 v100, v92, v102
	v_mul_f32_e32 v100, 0xbfb8aa3b, v100
	v_exp_f32_e32 v100, v100
	s_nop 0
	v_add_f32_e32 v100, 1.0, v100
	v_div_scale_f32 v101, s[90:91], v100, v100, 1.0
	v_rcp_f32_e32 v103, v101
	v_div_scale_f32 v106, vcc, 1.0, v100, 1.0
	v_fma_f32 v107, -v101, v103, 1.0
	v_fmac_f32_e32 v103, v107, v103
	v_mul_f32_e32 v107, v106, v103
	v_fma_f32 v108, -v101, v107, v106
	v_fmac_f32_e32 v107, v108, v103
	v_fma_f32 v101, -v101, v107, v106
	v_div_fmas_f32 v101, v101, v103, v107
	v_div_fixup_f32 v100, v101, v100, 1.0
	global_store_dword v[98:99], v100, off offset:24
	v_mov_b32_e32 v100, v253
	v_fmac_f32_e32 v100, v93, v102
	v_mul_f32_e32 v100, 0xbfb8aa3b, v100
	v_exp_f32_e32 v100, v100
	s_nop 0
	v_add_f32_e32 v100, 1.0, v100
	v_div_scale_f32 v101, s[90:91], v100, v100, 1.0
	v_rcp_f32_e32 v103, v101
	v_div_scale_f32 v106, vcc, 1.0, v100, 1.0
	v_fma_f32 v107, -v101, v103, 1.0
	v_fmac_f32_e32 v103, v107, v103
	v_mul_f32_e32 v107, v106, v103
	v_fma_f32 v108, -v101, v107, v106
	v_fmac_f32_e32 v107, v108, v103
	v_fma_f32 v101, -v101, v107, v106
	v_div_fmas_f32 v101, v101, v103, v107
	v_div_fixup_f32 v100, v101, v100, 1.0
	global_store_dword v[98:99], v100, off offset:28

.LBB0_718:
	v_or_b32_e32 v88, 48, v172
	v_ashrrev_i32_e32 v89, 31, v88
	v_lshl_add_u64 v[82:83], v[88:89], 2, s[0:1]
	global_load_dword v82, v[82:83], off
	s_and_b64 vcc, exec, s[10:11]
	s_waitcnt vmcnt(0)
	v_fmamk_f32 v82, v82, 0x3a800000, v155
	v_rsq_f32_e32 v86, v82
	s_cbranch_vccnz .LBB0_843
	s_and_b64 vcc, exec, s[8:9]
	s_mov_b64 s[12:13], -1
	s_cbranch_vccnz .LBB0_735
	s_andn2_b64 vcc, exec, s[84:85]
	s_cbranch_vccnz .LBB0_728
	s_andn2_b64 vcc, exec, s[34:35]
	s_cbranch_vccnz .LBB0_727
	v_readlane_b32 s12, v254, 58
	v_readlane_b32 s13, v254, 59
	v_readlane_b32 s44, v255, 0
	v_readlane_b32 s45, v255, 1
	v_mov_b64_e32 v[82:83], s[12:13]
	s_movk_i32 s12, 0x90
	v_mad_i64_i32 v[82:83], s[12:13], v88, s12, v[82:83]
	s_and_saveexec_b64 s[12:13], s[44:45]
	s_cbranch_execz .LBB0_724
	v_mov_b32_e32 v84, v246
	v_lshlrev_b32_e32 v142, 2, v146
	v_fmac_f32_e32 v84, v78, v86
	v_mul_f32_e32 v84, 0xbfb8aa3b, v84
	v_exp_f32_e32 v84, v84
	s_nop 0
	v_add_f32_e32 v87, 1.0, v84
	v_div_scale_f32 v90, s[90:91], v87, v87, 1.0
	v_rcp_f32_e32 v91, v90
	v_div_scale_f32 v92, vcc, 1.0, v87, 1.0
	v_lshl_add_u64 v[84:85], v[82:83], 0, v[142:143]
	v_fma_f32 v93, -v90, v91, 1.0
	v_fmac_f32_e32 v91, v93, v91
	v_mul_f32_e32 v93, v92, v91
	v_fma_f32 v94, -v90, v93, v92
	v_fmac_f32_e32 v93, v94, v91
	v_fma_f32 v90, -v90, v93, v92
	v_div_fmas_f32 v90, v90, v91, v93
	v_div_fixup_f32 v87, v90, v87, 1.0
	global_store_dword v[84:85], v87, off
	v_mov_b32_e32 v87, v247
	v_fmac_f32_e32 v87, v79, v86
	v_mul_f32_e32 v87, 0xbfb8aa3b, v87
	v_exp_f32_e32 v87, v87
	s_nop 0
	v_add_f32_e32 v87, 1.0, v87
	v_div_scale_f32 v90, s[90:91], v87, v87, 1.0
	v_rcp_f32_e32 v91, v90
	v_div_scale_f32 v92, vcc, 1.0, v87, 1.0
	v_fma_f32 v93, -v90, v91, 1.0
	v_fmac_f32_e32 v91, v93, v91
	v_mul_f32_e32 v93, v92, v91
	v_fma_f32 v94, -v90, v93, v92
	v_fmac_f32_e32 v93, v94, v91
	v_fma_f32 v90, -v90, v93, v92
	v_div_fmas_f32 v90, v90, v91, v93
	v_div_fixup_f32 v87, v90, v87, 1.0
	global_store_dword v[84:85], v87, off offset:4
	v_mov_b32_e32 v87, v248
	v_fmac_f32_e32 v87, v80, v86
	v_mul_f32_e32 v87, 0xbfb8aa3b, v87
	v_exp_f32_e32 v87, v87
	s_nop 0
	v_add_f32_e32 v87, 1.0, v87
	v_div_scale_f32 v90, s[90:91], v87, v87, 1.0
	v_rcp_f32_e32 v91, v90
	v_div_scale_f32 v92, vcc, 1.0, v87, 1.0
	v_fma_f32 v93, -v90, v91, 1.0
	v_fmac_f32_e32 v91, v93, v91
	v_mul_f32_e32 v93, v92, v91
	v_fma_f32 v94, -v90, v93, v92
	v_fmac_f32_e32 v93, v94, v91
	v_fma_f32 v90, -v90, v93, v92
	v_div_fmas_f32 v90, v90, v91, v93
	v_div_fixup_f32 v87, v90, v87, 1.0
	global_store_dword v[84:85], v87, off offset:8
	v_mov_b32_e32 v87, v249
	v_fmac_f32_e32 v87, v81, v86
	v_mul_f32_e32 v87, 0xbfb8aa3b, v87
	v_exp_f32_e32 v87, v87
	s_nop 0
	v_add_f32_e32 v87, 1.0, v87
	v_div_scale_f32 v90, s[90:91], v87, v87, 1.0
	v_rcp_f32_e32 v91, v90
	v_div_scale_f32 v92, vcc, 1.0, v87, 1.0
	v_fma_f32 v93, -v90, v91, 1.0
	v_fmac_f32_e32 v91, v93, v91
	v_mul_f32_e32 v93, v92, v91
	v_fma_f32 v94, -v90, v93, v92
	v_fmac_f32_e32 v93, v94, v91
	v_fma_f32 v90, -v90, v93, v92
	v_div_fmas_f32 v90, v90, v91, v93
	v_div_fixup_f32 v87, v90, v87, 1.0
	global_store_dword v[84:85], v87, off offset:12
.LBB0_724:
	s_or_b64 exec, exec, s[12:13]
	v_readlane_b32 s44, v255, 2
	v_readlane_b32 s45, v255, 3
	s_and_saveexec_b64 s[12:13], s[44:45]
	s_cbranch_execz .LBB0_726
	v_mov_b32_e32 v84, v250
	v_lshlrev_b32_e32 v142, 2, v146
	v_lshl_add_u64 v[82:83], v[82:83], 0, v[142:143]
	v_fmac_f32_e32 v84, v74, v86
	v_mul_f32_e32 v84, 0xbfb8aa3b, v84
	v_exp_f32_e32 v84, v84
	s_nop 0
	v_add_f32_e32 v84, 1.0, v84
	v_div_scale_f32 v85, s[90:91], v84, v84, 1.0
	v_rcp_f32_e32 v87, v85
	v_div_scale_f32 v90, vcc, 1.0, v84, 1.0
	v_fma_f32 v91, -v85, v87, 1.0
	v_fmac_f32_e32 v87, v91, v87
	v_mul_f32_e32 v91, v90, v87
	v_fma_f32 v92, -v85, v91, v90
	v_fmac_f32_e32 v91, v92, v87
	v_fma_f32 v85, -v85, v91, v90
	v_div_fmas_f32 v85, v85, v87, v91
	v_div_fixup_f32 v84, v85, v84, 1.0
	global_store_dword v[82:83], v84, off offset:16
	v_mov_b32_e32 v84, v251
	v_fmac_f32_e32 v84, v75, v86
	v_mul_f32_e32 v84, 0xbfb8aa3b, v84
	v_exp_f32_e32 v84, v84
	s_nop 0
	v_add_f32_e32 v84, 1.0, v84
	v_div_scale_f32 v85, s[90:91], v84, v84, 1.0
	v_rcp_f32_e32 v87, v85
	v_div_scale_f32 v90, vcc, 1.0, v84, 1.0
	v_fma_f32 v91, -v85, v87, 1.0
	v_fmac_f32_e32 v87, v91, v87
	v_mul_f32_e32 v91, v90, v87
	v_fma_f32 v92, -v85, v91, v90
	v_fmac_f32_e32 v91, v92, v87
	v_fma_f32 v85, -v85, v91, v90
	v_div_fmas_f32 v85, v85, v87, v91
	v_div_fixup_f32 v84, v85, v84, 1.0
	global_store_dword v[82:83], v84, off offset:20
	v_mov_b32_e32 v84, v252
	v_fmac_f32_e32 v84, v76, v86
	v_mul_f32_e32 v84, 0xbfb8aa3b, v84
	v_exp_f32_e32 v84, v84
	s_nop 0
	v_add_f32_e32 v84, 1.0, v84
	v_div_scale_f32 v85, s[90:91], v84, v84, 1.0
	v_rcp_f32_e32 v87, v85
	v_div_scale_f32 v90, vcc, 1.0, v84, 1.0
	v_fma_f32 v91, -v85, v87, 1.0
	v_fmac_f32_e32 v87, v91, v87
	v_mul_f32_e32 v91, v90, v87
	v_fma_f32 v92, -v85, v91, v90
	v_fmac_f32_e32 v91, v92, v87
	v_fma_f32 v85, -v85, v91, v90
	v_div_fmas_f32 v85, v85, v87, v91
	v_div_fixup_f32 v84, v85, v84, 1.0
	global_store_dword v[82:83], v84, off offset:24
	v_mov_b32_e32 v84, v253
	v_fmac_f32_e32 v84, v77, v86
	v_mul_f32_e32 v84, 0xbfb8aa3b, v84
	v_exp_f32_e32 v84, v84
	s_nop 0
	v_add_f32_e32 v84, 1.0, v84
	v_div_scale_f32 v85, s[90:91], v84, v84, 1.0
	v_rcp_f32_e32 v87, v85
	v_div_scale_f32 v90, vcc, 1.0, v84, 1.0
	v_fma_f32 v91, -v85, v87, 1.0
	v_fmac_f32_e32 v87, v91, v87
	v_mul_f32_e32 v91, v90, v87
	v_fma_f32 v92, -v85, v91, v90
	v_fmac_f32_e32 v91, v92, v87
	v_fma_f32 v85, -v85, v91, v90
	v_div_fmas_f32 v85, v85, v87, v91
	v_div_fixup_f32 v84, v85, v84, 1.0
	global_store_dword v[82:83], v84, off offset:28

.LBB0_742:
	global_load_dword v72, v[174:175], off offset:512
	v_add_u32_e32 v70, 0x80, v172
	v_ashrrev_i32_e32 v66, 6, v70
	v_ashrrev_i32_e32 v67, 31, v66
	v_lshlrev_b64 v[68:69], 13, v[66:67]
	v_lshl_add_u64 v[66:67], v[66:67], 0, s[74:75]
	v_lshlrev_b64 v[66:67], 13, v[66:67]
	v_ashrrev_i32_e32 v71, 31, v70
	s_and_b64 vcc, exec, s[10:11]
	s_waitcnt vmcnt(0)
	v_fmamk_f32 v72, v72, 0x3a800000, v155
	v_rsq_f32_e32 v72, v72
	s_cbranch_vccnz .LBB0_844
	s_and_b64 vcc, exec, s[8:9]
	s_mov_b64 s[12:13], -1
	s_cbranch_vccnz .LBB0_759
	s_andn2_b64 vcc, exec, s[84:85]
	s_cbranch_vccnz .LBB0_752
	s_andn2_b64 vcc, exec, s[34:35]
	s_cbranch_vccnz .LBB0_751
	v_readlane_b32 s12, v254, 58
	v_readlane_b32 s13, v254, 59
	v_readlane_b32 s44, v255, 0
	v_readlane_b32 s45, v255, 1
	v_mov_b64_e32 v[74:75], s[12:13]
	s_movk_i32 s12, 0x90
	v_mad_i64_i32 v[74:75], s[12:13], v70, s12, v[74:75]
	s_and_saveexec_b64 s[12:13], s[44:45]
	s_cbranch_execz .LBB0_748
	v_mov_b32_e32 v73, v246
	v_lshlrev_b32_e32 v142, 2, v146
	v_lshl_add_u64 v[76:77], v[74:75], 0, v[142:143]
	v_fmac_f32_e32 v73, v62, v72
	v_mul_f32_e32 v73, 0xbfb8aa3b, v73
	v_exp_f32_e32 v73, v73
	s_nop 0
	v_add_f32_e32 v73, 1.0, v73
	v_div_scale_f32 v78, s[86:87], v73, v73, 1.0
	v_rcp_f32_e32 v79, v78
	v_div_scale_f32 v80, vcc, 1.0, v73, 1.0
	v_fma_f32 v81, -v78, v79, 1.0
	v_fmac_f32_e32 v79, v81, v79
	v_mul_f32_e32 v81, v80, v79
	v_fma_f32 v82, -v78, v81, v80
	v_fmac_f32_e32 v81, v82, v79
	v_fma_f32 v78, -v78, v81, v80
	v_div_fmas_f32 v78, v78, v79, v81
	v_div_fixup_f32 v73, v78, v73, 1.0
	global_store_dword v[76:77], v73, off
	v_mov_b32_e32 v73, v247
	v_fmac_f32_e32 v73, v63, v72
	v_mul_f32_e32 v73, 0xbfb8aa3b, v73
	v_exp_f32_e32 v73, v73
	s_nop 0
	v_add_f32_e32 v73, 1.0, v73
	v_div_scale_f32 v78, s[86:87], v73, v73, 1.0
	v_rcp_f32_e32 v79, v78
	v_div_scale_f32 v80, vcc, 1.0, v73, 1.0
	v_fma_f32 v81, -v78, v79, 1.0
	v_fmac_f32_e32 v79, v81, v79
	v_mul_f32_e32 v81, v80, v79
	v_fma_f32 v82, -v78, v81, v80
	v_fmac_f32_e32 v81, v82, v79
	v_fma_f32 v78, -v78, v81, v80
	v_div_fmas_f32 v78, v78, v79, v81
	v_div_fixup_f32 v73, v78, v73, 1.0
	global_store_dword v[76:77], v73, off offset:4
	v_mov_b32_e32 v73, v248
	v_fmac_f32_e32 v73, v64, v72
	v_mul_f32_e32 v73, 0xbfb8aa3b, v73
	v_exp_f32_e32 v73, v73
	s_nop 0
	v_add_f32_e32 v73, 1.0, v73
	v_div_scale_f32 v78, s[86:87], v73, v73, 1.0
	v_rcp_f32_e32 v79, v78
	v_div_scale_f32 v80, vcc, 1.0, v73, 1.0
	v_fma_f32 v81, -v78, v79, 1.0
	v_fmac_f32_e32 v79, v81, v79
	v_mul_f32_e32 v81, v80, v79
	v_fma_f32 v82, -v78, v81, v80
	v_fmac_f32_e32 v81, v82, v79
	v_fma_f32 v78, -v78, v81, v80
	v_div_fmas_f32 v78, v78, v79, v81
	v_div_fixup_f32 v73, v78, v73, 1.0
	global_store_dword v[76:77], v73, off offset:8
	v_mov_b32_e32 v73, v249
	v_fmac_f32_e32 v73, v65, v72
	v_mul_f32_e32 v73, 0xbfb8aa3b, v73
	v_exp_f32_e32 v73, v73
	s_nop 0
	v_add_f32_e32 v73, 1.0, v73
	v_div_scale_f32 v78, s[86:87], v73, v73, 1.0
	v_rcp_f32_e32 v79, v78
	v_div_scale_f32 v80, vcc, 1.0, v73, 1.0
	v_fma_f32 v81, -v78, v79, 1.0
	v_fmac_f32_e32 v79, v81, v79
	v_mul_f32_e32 v81, v80, v79
	v_fma_f32 v82, -v78, v81, v80
	v_fmac_f32_e32 v81, v82, v79
	v_fma_f32 v78, -v78, v81, v80
	v_div_fmas_f32 v78, v78, v79, v81
	v_div_fixup_f32 v73, v78, v73, 1.0
	global_store_dword v[76:77], v73, off offset:12
.LBB0_748:
	s_or_b64 exec, exec, s[12:13]
	v_readlane_b32 s44, v255, 2
	v_readlane_b32 s45, v255, 3
	s_and_saveexec_b64 s[12:13], s[44:45]
	s_cbranch_execz .LBB0_750
	v_mov_b32_e32 v73, v250
	v_lshlrev_b32_e32 v142, 2, v146
	v_lshl_add_u64 v[74:75], v[74:75], 0, v[142:143]
	v_fmac_f32_e32 v73, v58, v72
	v_mul_f32_e32 v73, 0xbfb8aa3b, v73
	v_exp_f32_e32 v73, v73
	s_nop 0
	v_add_f32_e32 v73, 1.0, v73
	v_div_scale_f32 v76, s[86:87], v73, v73, 1.0
	v_rcp_f32_e32 v77, v76
	v_div_scale_f32 v78, vcc, 1.0, v73, 1.0
	v_fma_f32 v79, -v76, v77, 1.0
	v_fmac_f32_e32 v77, v79, v77
	v_mul_f32_e32 v79, v78, v77
	v_fma_f32 v80, -v76, v79, v78
	v_fmac_f32_e32 v79, v80, v77
	v_fma_f32 v76, -v76, v79, v78
	v_div_fmas_f32 v76, v76, v77, v79
	v_div_fixup_f32 v73, v76, v73, 1.0
	global_store_dword v[74:75], v73, off offset:16
	v_mov_b32_e32 v73, v251
	v_fmac_f32_e32 v73, v59, v72
	v_mul_f32_e32 v73, 0xbfb8aa3b, v73
	v_exp_f32_e32 v73, v73
	s_nop 0
	v_add_f32_e32 v73, 1.0, v73
	v_div_scale_f32 v76, s[86:87], v73, v73, 1.0
	v_rcp_f32_e32 v77, v76
	v_div_scale_f32 v78, vcc, 1.0, v73, 1.0
	v_fma_f32 v79, -v76, v77, 1.0
	v_fmac_f32_e32 v77, v79, v77
	v_mul_f32_e32 v79, v78, v77
	v_fma_f32 v80, -v76, v79, v78
	v_fmac_f32_e32 v79, v80, v77
	v_fma_f32 v76, -v76, v79, v78
	v_div_fmas_f32 v76, v76, v77, v79
	v_div_fixup_f32 v73, v76, v73, 1.0
	global_store_dword v[74:75], v73, off offset:20
	v_mov_b32_e32 v73, v252
	v_fmac_f32_e32 v73, v60, v72
	v_mul_f32_e32 v73, 0xbfb8aa3b, v73
	v_exp_f32_e32 v73, v73
	s_nop 0
	v_add_f32_e32 v73, 1.0, v73
	v_div_scale_f32 v76, s[86:87], v73, v73, 1.0
	v_rcp_f32_e32 v77, v76
	v_div_scale_f32 v78, vcc, 1.0, v73, 1.0
	v_fma_f32 v79, -v76, v77, 1.0
	v_fmac_f32_e32 v77, v79, v77
	v_mul_f32_e32 v79, v78, v77
	v_fma_f32 v80, -v76, v79, v78
	v_fmac_f32_e32 v79, v80, v77
	v_fma_f32 v76, -v76, v79, v78
	v_div_fmas_f32 v76, v76, v77, v79
	v_div_fixup_f32 v73, v76, v73, 1.0
	global_store_dword v[74:75], v73, off offset:24
	v_mov_b32_e32 v73, v253
	v_fmac_f32_e32 v73, v61, v72
	v_mul_f32_e32 v73, 0xbfb8aa3b, v73
	v_exp_f32_e32 v73, v73
	s_nop 0
	v_add_f32_e32 v73, 1.0, v73
	v_div_scale_f32 v76, s[86:87], v73, v73, 1.0
	v_rcp_f32_e32 v77, v76
	v_div_scale_f32 v78, vcc, 1.0, v73, 1.0
	v_fma_f32 v79, -v76, v77, 1.0
	v_fmac_f32_e32 v77, v79, v77
	v_mul_f32_e32 v79, v78, v77
	v_fma_f32 v80, -v76, v79, v78
	v_fmac_f32_e32 v79, v80, v77
	v_fma_f32 v76, -v76, v79, v78
	v_div_fmas_f32 v76, v76, v77, v79
	v_div_fixup_f32 v73, v76, v73, 1.0
	global_store_dword v[74:75], v73, off offset:28

.LBB0_766:
	global_load_dword v50, v[174:175], off offset:576
	v_add_u32_e32 v56, 0x90, v172
	s_and_b64 vcc, exec, s[10:11]
	v_ashrrev_i32_e32 v57, 31, v56
	s_waitcnt vmcnt(0)
	v_fmamk_f32 v50, v50, 0x3a800000, v155
	v_rsq_f32_e32 v54, v50
	s_cbranch_vccnz .LBB0_845
	s_and_b64 vcc, exec, s[8:9]
	s_mov_b64 s[12:13], -1
	s_cbranch_vccnz .LBB0_783
	s_andn2_b64 vcc, exec, s[84:85]
	s_cbranch_vccnz .LBB0_776
	s_andn2_b64 vcc, exec, s[34:35]
	s_cbranch_vccnz .LBB0_775
	v_readlane_b32 s12, v254, 58
	v_readlane_b32 s13, v254, 59
	v_readlane_b32 s44, v255, 0
	v_readlane_b32 s45, v255, 1
	v_mov_b64_e32 v[50:51], s[12:13]
	s_movk_i32 s12, 0x90
	v_mad_i64_i32 v[50:51], s[12:13], v56, s12, v[50:51]
	s_and_saveexec_b64 s[12:13], s[44:45]
	s_cbranch_execz .LBB0_772
	v_mov_b32_e32 v52, v246
	v_lshlrev_b32_e32 v142, 2, v146
	v_fmac_f32_e32 v52, v46, v54
	v_mul_f32_e32 v52, 0xbfb8aa3b, v52
	v_exp_f32_e32 v52, v52
	s_nop 0
	v_add_f32_e32 v55, 1.0, v52
	v_div_scale_f32 v58, s[86:87], v55, v55, 1.0
	v_rcp_f32_e32 v59, v58
	v_div_scale_f32 v60, vcc, 1.0, v55, 1.0
	v_lshl_add_u64 v[52:53], v[50:51], 0, v[142:143]
	v_fma_f32 v61, -v58, v59, 1.0
	v_fmac_f32_e32 v59, v61, v59
	v_mul_f32_e32 v61, v60, v59
	v_fma_f32 v62, -v58, v61, v60
	v_fmac_f32_e32 v61, v62, v59
	v_fma_f32 v58, -v58, v61, v60
	v_div_fmas_f32 v58, v58, v59, v61
	v_div_fixup_f32 v55, v58, v55, 1.0
	global_store_dword v[52:53], v55, off
	v_mov_b32_e32 v55, v247
	v_fmac_f32_e32 v55, v47, v54
	v_mul_f32_e32 v55, 0xbfb8aa3b, v55
	v_exp_f32_e32 v55, v55
	s_nop 0
	v_add_f32_e32 v55, 1.0, v55
	v_div_scale_f32 v58, s[86:87], v55, v55, 1.0
	v_rcp_f32_e32 v59, v58
	v_div_scale_f32 v60, vcc, 1.0, v55, 1.0
	v_fma_f32 v61, -v58, v59, 1.0
	v_fmac_f32_e32 v59, v61, v59
	v_mul_f32_e32 v61, v60, v59
	v_fma_f32 v62, -v58, v61, v60
	v_fmac_f32_e32 v61, v62, v59
	v_fma_f32 v58, -v58, v61, v60
	v_div_fmas_f32 v58, v58, v59, v61
	v_div_fixup_f32 v55, v58, v55, 1.0
	global_store_dword v[52:53], v55, off offset:4
	v_mov_b32_e32 v55, v248
	v_fmac_f32_e32 v55, v48, v54
	v_mul_f32_e32 v55, 0xbfb8aa3b, v55
	v_exp_f32_e32 v55, v55
	s_nop 0
	v_add_f32_e32 v55, 1.0, v55
	v_div_scale_f32 v58, s[86:87], v55, v55, 1.0
	v_rcp_f32_e32 v59, v58
	v_div_scale_f32 v60, vcc, 1.0, v55, 1.0
	v_fma_f32 v61, -v58, v59, 1.0
	v_fmac_f32_e32 v59, v61, v59
	v_mul_f32_e32 v61, v60, v59
	v_fma_f32 v62, -v58, v61, v60
	v_fmac_f32_e32 v61, v62, v59
	v_fma_f32 v58, -v58, v61, v60
	v_div_fmas_f32 v58, v58, v59, v61
	v_div_fixup_f32 v55, v58, v55, 1.0
	global_store_dword v[52:53], v55, off offset:8
	v_mov_b32_e32 v55, v249
	v_fmac_f32_e32 v55, v49, v54
	v_mul_f32_e32 v55, 0xbfb8aa3b, v55
	v_exp_f32_e32 v55, v55
	s_nop 0
	v_add_f32_e32 v55, 1.0, v55
	v_div_scale_f32 v58, s[86:87], v55, v55, 1.0
	v_rcp_f32_e32 v59, v58
	v_div_scale_f32 v60, vcc, 1.0, v55, 1.0
	v_fma_f32 v61, -v58, v59, 1.0
	v_fmac_f32_e32 v59, v61, v59
	v_mul_f32_e32 v61, v60, v59
	v_fma_f32 v62, -v58, v61, v60
	v_fmac_f32_e32 v61, v62, v59
	v_fma_f32 v58, -v58, v61, v60
	v_div_fmas_f32 v58, v58, v59, v61
	v_div_fixup_f32 v55, v58, v55, 1.0
	global_store_dword v[52:53], v55, off offset:12
.LBB0_772:
	s_or_b64 exec, exec, s[12:13]
	v_readlane_b32 s44, v255, 2
	v_readlane_b32 s45, v255, 3
	s_and_saveexec_b64 s[12:13], s[44:45]
	s_cbranch_execz .LBB0_774
	v_mov_b32_e32 v52, v250
	v_lshlrev_b32_e32 v142, 2, v146
	v_lshl_add_u64 v[50:51], v[50:51], 0, v[142:143]
	v_fmac_f32_e32 v52, v42, v54
	v_mul_f32_e32 v52, 0xbfb8aa3b, v52
	v_exp_f32_e32 v52, v52
	s_nop 0
	v_add_f32_e32 v52, 1.0, v52
	v_div_scale_f32 v53, s[86:87], v52, v52, 1.0
	v_rcp_f32_e32 v55, v53
	v_div_scale_f32 v58, vcc, 1.0, v52, 1.0
	v_fma_f32 v59, -v53, v55, 1.0
	v_fmac_f32_e32 v55, v59, v55
	v_mul_f32_e32 v59, v58, v55
	v_fma_f32 v60, -v53, v59, v58
	v_fmac_f32_e32 v59, v60, v55
	v_fma_f32 v53, -v53, v59, v58
	v_div_fmas_f32 v53, v53, v55, v59
	v_div_fixup_f32 v52, v53, v52, 1.0
	global_store_dword v[50:51], v52, off offset:16
	v_mov_b32_e32 v52, v251
	v_fmac_f32_e32 v52, v43, v54
	v_mul_f32_e32 v52, 0xbfb8aa3b, v52
	v_exp_f32_e32 v52, v52
	s_nop 0
	v_add_f32_e32 v52, 1.0, v52
	v_div_scale_f32 v53, s[86:87], v52, v52, 1.0
	v_rcp_f32_e32 v55, v53
	v_div_scale_f32 v58, vcc, 1.0, v52, 1.0
	v_fma_f32 v59, -v53, v55, 1.0
	v_fmac_f32_e32 v55, v59, v55
	v_mul_f32_e32 v59, v58, v55
	v_fma_f32 v60, -v53, v59, v58
	v_fmac_f32_e32 v59, v60, v55
	v_fma_f32 v53, -v53, v59, v58
	v_div_fmas_f32 v53, v53, v55, v59
	v_div_fixup_f32 v52, v53, v52, 1.0
	global_store_dword v[50:51], v52, off offset:20
	v_mov_b32_e32 v52, v252
	v_fmac_f32_e32 v52, v44, v54
	v_mul_f32_e32 v52, 0xbfb8aa3b, v52
	v_exp_f32_e32 v52, v52
	s_nop 0
	v_add_f32_e32 v52, 1.0, v52
	v_div_scale_f32 v53, s[86:87], v52, v52, 1.0
	v_rcp_f32_e32 v55, v53
	v_div_scale_f32 v58, vcc, 1.0, v52, 1.0
	v_fma_f32 v59, -v53, v55, 1.0
	v_fmac_f32_e32 v55, v59, v55
	v_mul_f32_e32 v59, v58, v55
	v_fma_f32 v60, -v53, v59, v58
	v_fmac_f32_e32 v59, v60, v55
	v_fma_f32 v53, -v53, v59, v58
	v_div_fmas_f32 v53, v53, v55, v59
	v_div_fixup_f32 v52, v53, v52, 1.0
	global_store_dword v[50:51], v52, off offset:24
	v_mov_b32_e32 v52, v253
	v_fmac_f32_e32 v52, v45, v54
	v_mul_f32_e32 v52, 0xbfb8aa3b, v52
	v_exp_f32_e32 v52, v52
	s_nop 0
	v_add_f32_e32 v52, 1.0, v52
	v_div_scale_f32 v53, s[86:87], v52, v52, 1.0
	v_rcp_f32_e32 v55, v53
	v_div_scale_f32 v58, vcc, 1.0, v52, 1.0
	v_fma_f32 v59, -v53, v55, 1.0
	v_fmac_f32_e32 v55, v59, v55
	v_mul_f32_e32 v59, v58, v55
	v_fma_f32 v60, -v53, v59, v58
	v_fmac_f32_e32 v59, v60, v55
	v_fma_f32 v53, -v53, v59, v58
	v_div_fmas_f32 v53, v53, v55, v59
	v_div_fixup_f32 v52, v53, v52, 1.0
	global_store_dword v[50:51], v52, off offset:28

.LBB0_790:
	global_load_dword v34, v[174:175], off offset:640
	v_add_u32_e32 v40, 0xa0, v172
	s_and_b64 vcc, exec, s[10:11]
	v_ashrrev_i32_e32 v41, 31, v40
	s_waitcnt vmcnt(0)
	v_fmamk_f32 v34, v34, 0x3a800000, v155
	v_rsq_f32_e32 v38, v34
	s_cbranch_vccnz .LBB0_846
	s_and_b64 vcc, exec, s[8:9]
	s_mov_b64 s[12:13], -1
	s_cbranch_vccnz .LBB0_807
	s_andn2_b64 vcc, exec, s[84:85]
	s_cbranch_vccnz .LBB0_800
	s_andn2_b64 vcc, exec, s[34:35]
	s_cbranch_vccnz .LBB0_799
	v_readlane_b32 s12, v254, 58
	v_readlane_b32 s13, v254, 59
	v_readlane_b32 s44, v255, 0
	v_readlane_b32 s45, v255, 1
	v_mov_b64_e32 v[34:35], s[12:13]
	s_movk_i32 s12, 0x90
	v_mad_i64_i32 v[34:35], s[12:13], v40, s12, v[34:35]
	s_and_saveexec_b64 s[12:13], s[44:45]
	s_cbranch_execz .LBB0_796
	v_mov_b32_e32 v36, v246
	v_lshlrev_b32_e32 v142, 2, v146
	v_fmac_f32_e32 v36, v30, v38
	v_mul_f32_e32 v36, 0xbfb8aa3b, v36
	v_exp_f32_e32 v36, v36
	s_nop 0
	v_add_f32_e32 v39, 1.0, v36
	v_div_scale_f32 v42, s[86:87], v39, v39, 1.0
	v_rcp_f32_e32 v43, v42
	v_div_scale_f32 v44, vcc, 1.0, v39, 1.0
	v_lshl_add_u64 v[36:37], v[34:35], 0, v[142:143]
	v_fma_f32 v45, -v42, v43, 1.0
	v_fmac_f32_e32 v43, v45, v43
	v_mul_f32_e32 v45, v44, v43
	v_fma_f32 v46, -v42, v45, v44
	v_fmac_f32_e32 v45, v46, v43
	v_fma_f32 v42, -v42, v45, v44
	v_div_fmas_f32 v42, v42, v43, v45
	v_div_fixup_f32 v39, v42, v39, 1.0
	global_store_dword v[36:37], v39, off
	v_mov_b32_e32 v39, v247
	v_fmac_f32_e32 v39, v31, v38
	v_mul_f32_e32 v39, 0xbfb8aa3b, v39
	v_exp_f32_e32 v39, v39
	s_nop 0
	v_add_f32_e32 v39, 1.0, v39
	v_div_scale_f32 v42, s[86:87], v39, v39, 1.0
	v_rcp_f32_e32 v43, v42
	v_div_scale_f32 v44, vcc, 1.0, v39, 1.0
	v_fma_f32 v45, -v42, v43, 1.0
	v_fmac_f32_e32 v43, v45, v43
	v_mul_f32_e32 v45, v44, v43
	v_fma_f32 v46, -v42, v45, v44
	v_fmac_f32_e32 v45, v46, v43
	v_fma_f32 v42, -v42, v45, v44
	v_div_fmas_f32 v42, v42, v43, v45
	v_div_fixup_f32 v39, v42, v39, 1.0
	global_store_dword v[36:37], v39, off offset:4
	v_mov_b32_e32 v39, v248
	v_fmac_f32_e32 v39, v32, v38
	v_mul_f32_e32 v39, 0xbfb8aa3b, v39
	v_exp_f32_e32 v39, v39
	s_nop 0
	v_add_f32_e32 v39, 1.0, v39
	v_div_scale_f32 v42, s[86:87], v39, v39, 1.0
	v_rcp_f32_e32 v43, v42
	v_div_scale_f32 v44, vcc, 1.0, v39, 1.0
	v_fma_f32 v45, -v42, v43, 1.0
	v_fmac_f32_e32 v43, v45, v43
	v_mul_f32_e32 v45, v44, v43
	v_fma_f32 v46, -v42, v45, v44
	v_fmac_f32_e32 v45, v46, v43
	v_fma_f32 v42, -v42, v45, v44
	v_div_fmas_f32 v42, v42, v43, v45
	v_div_fixup_f32 v39, v42, v39, 1.0
	global_store_dword v[36:37], v39, off offset:8
	v_mov_b32_e32 v39, v249
	v_fmac_f32_e32 v39, v33, v38
	v_mul_f32_e32 v39, 0xbfb8aa3b, v39
	v_exp_f32_e32 v39, v39
	s_nop 0
	v_add_f32_e32 v39, 1.0, v39
	v_div_scale_f32 v42, s[86:87], v39, v39, 1.0
	v_rcp_f32_e32 v43, v42
	v_div_scale_f32 v44, vcc, 1.0, v39, 1.0
	v_fma_f32 v45, -v42, v43, 1.0
	v_fmac_f32_e32 v43, v45, v43
	v_mul_f32_e32 v45, v44, v43
	v_fma_f32 v46, -v42, v45, v44
	v_fmac_f32_e32 v45, v46, v43
	v_fma_f32 v42, -v42, v45, v44
	v_div_fmas_f32 v42, v42, v43, v45
	v_div_fixup_f32 v39, v42, v39, 1.0
	global_store_dword v[36:37], v39, off offset:12
.LBB0_796:
	s_or_b64 exec, exec, s[12:13]
	v_readlane_b32 s44, v255, 2
	v_readlane_b32 s45, v255, 3
	s_and_saveexec_b64 s[12:13], s[44:45]
	s_cbranch_execz .LBB0_798
	v_mov_b32_e32 v36, v250
	v_lshlrev_b32_e32 v142, 2, v146
	v_lshl_add_u64 v[34:35], v[34:35], 0, v[142:143]
	v_fmac_f32_e32 v36, v26, v38
	v_mul_f32_e32 v36, 0xbfb8aa3b, v36
	v_exp_f32_e32 v36, v36
	s_nop 0
	v_add_f32_e32 v36, 1.0, v36
	v_div_scale_f32 v37, s[86:87], v36, v36, 1.0
	v_rcp_f32_e32 v39, v37
	v_div_scale_f32 v42, vcc, 1.0, v36, 1.0
	v_fma_f32 v43, -v37, v39, 1.0
	v_fmac_f32_e32 v39, v43, v39
	v_mul_f32_e32 v43, v42, v39
	v_fma_f32 v44, -v37, v43, v42
	v_fmac_f32_e32 v43, v44, v39
	v_fma_f32 v37, -v37, v43, v42
	v_div_fmas_f32 v37, v37, v39, v43
	v_div_fixup_f32 v36, v37, v36, 1.0
	global_store_dword v[34:35], v36, off offset:16
	v_mov_b32_e32 v36, v251
	v_fmac_f32_e32 v36, v27, v38
	v_mul_f32_e32 v36, 0xbfb8aa3b, v36
	v_exp_f32_e32 v36, v36
	s_nop 0
	v_add_f32_e32 v36, 1.0, v36
	v_div_scale_f32 v37, s[86:87], v36, v36, 1.0
	v_rcp_f32_e32 v39, v37
	v_div_scale_f32 v42, vcc, 1.0, v36, 1.0
	v_fma_f32 v43, -v37, v39, 1.0
	v_fmac_f32_e32 v39, v43, v39
	v_mul_f32_e32 v43, v42, v39
	v_fma_f32 v44, -v37, v43, v42
	v_fmac_f32_e32 v43, v44, v39
	v_fma_f32 v37, -v37, v43, v42
	v_div_fmas_f32 v37, v37, v39, v43
	v_div_fixup_f32 v36, v37, v36, 1.0
	global_store_dword v[34:35], v36, off offset:20
	v_mov_b32_e32 v36, v252
	v_fmac_f32_e32 v36, v28, v38
	v_mul_f32_e32 v36, 0xbfb8aa3b, v36
	v_exp_f32_e32 v36, v36
	s_nop 0
	v_add_f32_e32 v36, 1.0, v36
	v_div_scale_f32 v37, s[86:87], v36, v36, 1.0
	v_rcp_f32_e32 v39, v37
	v_div_scale_f32 v42, vcc, 1.0, v36, 1.0
	v_fma_f32 v43, -v37, v39, 1.0
	v_fmac_f32_e32 v39, v43, v39
	v_mul_f32_e32 v43, v42, v39
	v_fma_f32 v44, -v37, v43, v42
	v_fmac_f32_e32 v43, v44, v39
	v_fma_f32 v37, -v37, v43, v42
	v_div_fmas_f32 v37, v37, v39, v43
	v_div_fixup_f32 v36, v37, v36, 1.0
	global_store_dword v[34:35], v36, off offset:24
	v_mov_b32_e32 v36, v253
	v_fmac_f32_e32 v36, v29, v38
	v_mul_f32_e32 v36, 0xbfb8aa3b, v36
	v_exp_f32_e32 v36, v36
	s_nop 0
	v_add_f32_e32 v36, 1.0, v36
	v_div_scale_f32 v37, s[86:87], v36, v36, 1.0
	v_rcp_f32_e32 v39, v37
	v_div_scale_f32 v42, vcc, 1.0, v36, 1.0
	v_fma_f32 v43, -v37, v39, 1.0
	v_fmac_f32_e32 v39, v43, v39
	v_mul_f32_e32 v43, v42, v39
	v_fma_f32 v44, -v37, v43, v42
	v_fmac_f32_e32 v43, v44, v39
	v_fma_f32 v37, -v37, v43, v42
	v_div_fmas_f32 v37, v37, v39, v43
	v_div_fixup_f32 v36, v37, v36, 1.0
	global_store_dword v[34:35], v36, off offset:28

.LBB0_814:
	global_load_dword v18, v[174:175], off offset:704
	v_add_u32_e32 v24, 0xb0, v172
	s_and_b64 vcc, exec, s[10:11]
	v_ashrrev_i32_e32 v25, 31, v24
	s_waitcnt vmcnt(0)
	v_fmamk_f32 v18, v18, 0x3a800000, v155
	v_rsq_f32_e32 v22, v18
	s_cbranch_vccnz .LBB0_847
	s_and_b64 vcc, exec, s[8:9]
	s_mov_b64 s[8:9], -1
	s_cbranch_vccnz .LBB0_831
	s_andn2_b64 vcc, exec, s[84:85]
	s_cbranch_vccnz .LBB0_824
	s_andn2_b64 vcc, exec, s[34:35]
	s_cbranch_vccnz .LBB0_823
	v_readlane_b32 s8, v254, 58
	v_readlane_b32 s9, v254, 59
	v_lshlrev_b32_e32 v142, 2, v146
	s_nop 0
	v_mov_b64_e32 v[18:19], s[8:9]
	s_movk_i32 s8, 0x90
	v_mad_i64_i32 v[18:19], s[8:9], v24, s8, v[18:19]
	s_mov_b64 s[8:9], exec
	v_readlane_b32 s10, v255, 0
	v_readlane_b32 s11, v255, 1
	s_and_b64 s[10:11], s[8:9], s[10:11]
	s_mov_b64 exec, s[10:11]
	s_cbranch_execz .LBB0_820
	v_mov_b32_e32 v20, v246
	v_fmac_f32_e32 v20, v14, v22
	v_mul_f32_e32 v20, 0xbfb8aa3b, v20
	v_exp_f32_e32 v20, v20
	s_nop 0
	v_add_f32_e32 v23, 1.0, v20
	v_div_scale_f32 v26, s[10:11], v23, v23, 1.0
	v_rcp_f32_e32 v27, v26
	v_div_scale_f32 v28, vcc, 1.0, v23, 1.0
	v_lshl_add_u64 v[20:21], v[18:19], 0, v[142:143]
	v_fma_f32 v29, -v26, v27, 1.0
	v_fmac_f32_e32 v27, v29, v27
	v_mul_f32_e32 v29, v28, v27
	v_fma_f32 v30, -v26, v29, v28
	v_fmac_f32_e32 v29, v30, v27
	v_fma_f32 v26, -v26, v29, v28
	v_div_fmas_f32 v26, v26, v27, v29
	v_div_fixup_f32 v23, v26, v23, 1.0
	global_store_dword v[20:21], v23, off
	v_mov_b32_e32 v23, v247
	v_fmac_f32_e32 v23, v15, v22
	v_mul_f32_e32 v23, 0xbfb8aa3b, v23
	v_exp_f32_e32 v23, v23
	s_nop 0
	v_add_f32_e32 v23, 1.0, v23
	v_div_scale_f32 v26, s[10:11], v23, v23, 1.0
	v_rcp_f32_e32 v27, v26
	v_div_scale_f32 v28, vcc, 1.0, v23, 1.0
	v_fma_f32 v29, -v26, v27, 1.0
	v_fmac_f32_e32 v27, v29, v27
	v_mul_f32_e32 v29, v28, v27
	v_fma_f32 v30, -v26, v29, v28
	v_fmac_f32_e32 v29, v30, v27
	v_fma_f32 v26, -v26, v29, v28
	v_div_fmas_f32 v26, v26, v27, v29
	v_div_fixup_f32 v23, v26, v23, 1.0
	global_store_dword v[20:21], v23, off offset:4
	v_mov_b32_e32 v23, v248
	v_fmac_f32_e32 v23, v16, v22
	v_mul_f32_e32 v23, 0xbfb8aa3b, v23
	v_exp_f32_e32 v23, v23
	s_nop 0
	v_add_f32_e32 v23, 1.0, v23
	v_div_scale_f32 v26, s[10:11], v23, v23, 1.0
	v_rcp_f32_e32 v27, v26
	v_div_scale_f32 v28, vcc, 1.0, v23, 1.0
	v_fma_f32 v29, -v26, v27, 1.0
	v_fmac_f32_e32 v27, v29, v27
	v_mul_f32_e32 v29, v28, v27
	v_fma_f32 v30, -v26, v29, v28
	v_fmac_f32_e32 v29, v30, v27
	v_fma_f32 v26, -v26, v29, v28
	v_div_fmas_f32 v26, v26, v27, v29
	v_div_fixup_f32 v23, v26, v23, 1.0
	global_store_dword v[20:21], v23, off offset:8
	v_mov_b32_e32 v23, v249
	v_fmac_f32_e32 v23, v17, v22
	v_mul_f32_e32 v23, 0xbfb8aa3b, v23
	v_exp_f32_e32 v23, v23
	s_nop 0
	v_add_f32_e32 v23, 1.0, v23
	v_div_scale_f32 v26, s[10:11], v23, v23, 1.0
	v_rcp_f32_e32 v27, v26
	v_div_scale_f32 v28, vcc, 1.0, v23, 1.0
	v_fma_f32 v29, -v26, v27, 1.0
	v_fmac_f32_e32 v27, v29, v27
	v_mul_f32_e32 v29, v28, v27
	v_fma_f32 v30, -v26, v29, v28
	v_fmac_f32_e32 v29, v30, v27
	v_fma_f32 v26, -v26, v29, v28
	v_div_fmas_f32 v26, v26, v27, v29
	v_div_fixup_f32 v23, v26, v23, 1.0
	global_store_dword v[20:21], v23, off offset:12
.LBB0_820:
	s_or_b64 exec, exec, s[8:9]
	s_mov_b64 s[8:9], exec
	v_readlane_b32 s10, v255, 2
	v_readlane_b32 s11, v255, 3
	s_and_b64 s[10:11], s[8:9], s[10:11]
	s_mov_b64 exec, s[10:11]
	s_cbranch_execz .LBB0_822
	v_mov_b32_e32 v20, v250
	v_lshl_add_u64 v[18:19], v[18:19], 0, v[142:143]
	v_fmac_f32_e32 v20, v10, v22
	v_mul_f32_e32 v20, 0xbfb8aa3b, v20
	v_exp_f32_e32 v20, v20
	s_nop 0
	v_add_f32_e32 v20, 1.0, v20
	v_div_scale_f32 v21, s[10:11], v20, v20, 1.0
	v_rcp_f32_e32 v23, v21
	v_div_scale_f32 v26, vcc, 1.0, v20, 1.0
	v_fma_f32 v27, -v21, v23, 1.0
	v_fmac_f32_e32 v23, v27, v23
	v_mul_f32_e32 v27, v26, v23
	v_fma_f32 v28, -v21, v27, v26
	v_fmac_f32_e32 v27, v28, v23
	v_fma_f32 v21, -v21, v27, v26
	v_div_fmas_f32 v21, v21, v23, v27
	v_div_fixup_f32 v20, v21, v20, 1.0
	global_store_dword v[18:19], v20, off offset:16
	v_mov_b32_e32 v20, v251
	v_fmac_f32_e32 v20, v11, v22
	v_mul_f32_e32 v20, 0xbfb8aa3b, v20
	v_exp_f32_e32 v20, v20
	s_nop 0
	v_add_f32_e32 v20, 1.0, v20
	v_div_scale_f32 v21, s[10:11], v20, v20, 1.0
	v_rcp_f32_e32 v23, v21
	v_div_scale_f32 v26, vcc, 1.0, v20, 1.0
	v_fma_f32 v27, -v21, v23, 1.0
	v_fmac_f32_e32 v23, v27, v23
	v_mul_f32_e32 v27, v26, v23
	v_fma_f32 v28, -v21, v27, v26
	v_fmac_f32_e32 v27, v28, v23
	v_fma_f32 v21, -v21, v27, v26
	v_div_fmas_f32 v21, v21, v23, v27
	v_div_fixup_f32 v20, v21, v20, 1.0
	global_store_dword v[18:19], v20, off offset:20
	v_mov_b32_e32 v20, v252
	v_fmac_f32_e32 v20, v12, v22
	v_mul_f32_e32 v20, 0xbfb8aa3b, v20
	v_exp_f32_e32 v20, v20
	s_nop 0
	v_add_f32_e32 v20, 1.0, v20
	v_div_scale_f32 v21, s[10:11], v20, v20, 1.0
	v_rcp_f32_e32 v23, v21
	v_div_scale_f32 v26, vcc, 1.0, v20, 1.0
	v_fma_f32 v27, -v21, v23, 1.0
	v_fmac_f32_e32 v23, v27, v23
	v_mul_f32_e32 v27, v26, v23
	v_fma_f32 v28, -v21, v27, v26
	v_fmac_f32_e32 v27, v28, v23
	v_fma_f32 v21, -v21, v27, v26
	v_div_fmas_f32 v21, v21, v23, v27
	v_div_fixup_f32 v20, v21, v20, 1.0
	global_store_dword v[18:19], v20, off offset:24
	v_mov_b32_e32 v20, v253
	v_fmac_f32_e32 v20, v13, v22
	v_mul_f32_e32 v20, 0xbfb8aa3b, v20
	v_exp_f32_e32 v20, v20
	s_nop 0
	v_add_f32_e32 v20, 1.0, v20
	v_div_scale_f32 v21, s[10:11], v20, v20, 1.0
	v_rcp_f32_e32 v23, v21
	v_div_scale_f32 v26, vcc, 1.0, v20, 1.0
	v_fma_f32 v27, -v21, v23, 1.0
	v_fmac_f32_e32 v23, v27, v23
	v_mul_f32_e32 v27, v26, v23
	v_fma_f32 v28, -v21, v27, v26
	v_fmac_f32_e32 v27, v28, v23
	v_fma_f32 v21, -v21, v27, v26
	v_div_fmas_f32 v21, v21, v23, v27
	v_div_fixup_f32 v20, v21, v20, 1.0
	global_store_dword v[18:19], v20, off offset:28
